# P2 queue order q7: 4 super-rounds of {2 LRU levels, 128 attnA, 2 LRU levels} then MoBA longest-first, so consecutive LRU levels do not wait on a carry ripple
# speedup vs baseline: 1.0174x; 1.0058x over previous
; __global__ void __launch_bounds__(512) hybrid_fwd(Params p) {
;     ...
;             const int u = s_unit;
;             __syncthreads();
;             if (u >= 1024 + 1024 + 512) break;
;             const int v2 = u - 512, grpq = v2 >> 7, rq = v2 & 127;
;     ...
;             if (u >= 512 && rq < 64) lru_unit(C, p, l, grpq * 64 + rq);
;     ...
;             if (u >= 512 && rq >= 64) moba_unit(C, grpq * 64 + (rq - 64), (const float*)(C.ws + WS_KM) + (size_t)l * 128 * 512);
;     ...
;             if (u < 512) attnA_unit(C, u);
.LBB0_321:
	s_or_b64 exec, exec, s[40:41]
	s_waitcnt lgkmcnt(0)
	s_barrier
	ds_read_b32 v0, v193
	s_movk_i32 s19, 0x9ff
	s_mov_b64 s[40:41], -1
	s_waitcnt lgkmcnt(0)
	s_barrier
	v_cmp_lt_i32_e32 vcc, s19, v0
	v_readfirstlane_b32 s74, v0
	s_cbranch_vccnz .LBB0_316
	s_cmp_lt_u32 s74, 1536
	s_cbranch_scc0 .Lq4_c
	s_lshr_b32 s19, s74, 7
	s_mul_i32 s20, s19, 11
	s_lshr_b32 s20, s20, 5
	s_mul_i32 s21, s20, 3
	s_sub_u32 s19, s19, s21
	s_and_b32 s22, s74, 127
	s_cmp_eq_u32 s19, 1
	s_cbranch_scc1 .Lq7_attn
	s_lshl_b32 s21, s20, 2
	s_add_u32 s21, s21, s19
	s_lshr_b32 s19, s22, 6
	s_add_u32 s21, s21, s19
	s_and_b32 s22, s22, 63
	s_lshl_b32 s21, s21, 7
	s_add_u32 s74, s21, s22
	s_add_u32 s74, s74, 512
	s_branch .Lq4_done
.Lq7_attn:
	s_lshl_b32 s20, s20, 7
	s_add_u32 s74, s20, s22
	s_branch .Lq4_done
